# norm loop: moved vmcnt(0) wait from before the wave reduction to first consumer of the mod vectors
# baseline (speedup 1.0000x reference)
.LBB0_545:
	v_pk_mul_f32 v[70:71], v[116:117], v[116:117]
	v_pk_mul_f32 v[72:73], v[112:113], v[112:113]
	v_pk_mul_f32 v[66:67], v[114:115], v[114:115]
	v_pk_mul_f32 v[68:69], v[110:111], v[110:111]
	v_pk_mov_b32 v[74:75], v[72:73], v[70:71] op_sel:[1,0]
	v_mov_b32_e32 v73, v71
	v_pk_add_f32 v[70:71], v[74:75], v[72:73]
	v_pk_mov_b32 v[72:73], v[68:69], v[66:67] op_sel:[1,0]
	v_mov_b32_e32 v69, v67
	v_pk_add_f32 v[66:67], v[72:73], v[68:69]
	v_pk_add_f32 v[70:71], v[70:71], v[70:71] op_sel_hi:[0,1]
	v_pk_add_f32 v[66:67], v[66:67], v[66:67] op_sel_hi:[0,1]
	v_mul_f32_e32 v66, v106, v106
	v_pk_fma_f32 v[68:69], v[106:107], v[106:107], v[66:67] op_sel_hi:[1,1,0]
	v_mul_f32_e32 v66, v108, v108
	v_pk_fma_f32 v[72:73], v[108:109], v[108:109], v[66:67] op_sel_hi:[1,1,0]
	v_mul_f32_e32 v68, v102, v102
	v_mul_f32_e32 v72, v103, v103
	v_mul_f32_e32 v70, v104, v104
	v_mul_f32_e32 v66, v105, v105
	v_pk_add_f32 v[68:69], v[68:69], v[72:73]
	v_pk_add_f32 v[66:67], v[70:71], v[66:67]
	v_cmp_lt_i32_e32 vcc, v221, v220
	v_pk_add_f32 v[66:67], v[68:69], v[66:67]
	v_add_f32_e32 v66, v66, v67
	v_cndmask_b32_e32 v67, v218, v221, vcc
	v_lshlrev_b32_e32 v67, 2, v67
	ds_bpermute_b32 v67, v67, v66
	v_cmp_lt_i32_e32 vcc, v222, v220
	s_waitcnt lgkmcnt(0)
	v_add_f32_e32 v66, v66, v67
	v_cndmask_b32_e32 v67, v218, v222, vcc
	v_lshlrev_b32_e32 v67, 2, v67
	ds_bpermute_b32 v67, v67, v66
	v_cmp_lt_i32_e32 vcc, v223, v220
	s_waitcnt lgkmcnt(0)
	v_add_f32_e32 v66, v66, v67
	v_cndmask_b32_e32 v67, v218, v223, vcc
	v_lshlrev_b32_e32 v67, 2, v67
	ds_bpermute_b32 v67, v67, v66
	v_cmp_lt_i32_e32 vcc, v224, v220
	s_waitcnt lgkmcnt(0)
	v_add_f32_e32 v66, v66, v67
	v_cndmask_b32_e32 v67, v218, v224, vcc
	v_lshlrev_b32_e32 v67, 2, v67
	ds_bpermute_b32 v67, v67, v66
	v_cmp_lt_i32_e32 vcc, v225, v220
	s_waitcnt lgkmcnt(0)
	v_add_f32_e32 v66, v66, v67
	v_cndmask_b32_e32 v67, v218, v225, vcc
	v_lshlrev_b32_e32 v67, 2, v67
	ds_bpermute_b32 v67, v67, v66
	v_cmp_lt_i32_e32 vcc, v226, v220
	s_waitcnt lgkmcnt(0)
	v_add_f32_e32 v66, v66, v67
	v_cndmask_b32_e32 v67, v218, v226, vcc
	v_lshlrev_b32_e32 v67, 2, v67
	ds_bpermute_b32 v67, v67, v66
	s_waitcnt lgkmcnt(0)
	v_add_f32_e32 v66, v66, v67
	v_fmamk_f32 v66, v66, 0x3a800000, v209
	v_mul_f32_e32 v67, 0x4f800000, v66
	v_cmp_gt_f32_e32 vcc, s23, v66
	s_nop 1
	v_cndmask_b32_e32 v66, v66, v67, vcc
	v_sqrt_f32_e32 v67, v66
	s_nop 0
	v_add_u32_e32 v68, -1, v67
	v_fma_f32 v69, -v68, v67, v66
	v_cmp_ge_f32_e64 s[42:43], 0, v69
	v_add_u32_e32 v69, 1, v67
	s_nop 0
	v_cndmask_b32_e64 v68, v67, v68, s[42:43]
	v_fma_f32 v67, -v69, v67, v66
	v_cmp_lt_f32_e64 s[42:43], 0, v67
	s_nop 1
	v_cndmask_b32_e64 v67, v68, v69, s[42:43]
	v_mul_f32_e32 v68, 0x37800000, v67
	v_cndmask_b32_e32 v67, v67, v68, vcc
	v_cmp_class_f32_e32 vcc, v66, v210
	s_nop 1
	v_cndmask_b32_e32 v66, v67, v66, vcc
	v_div_scale_f32 v67, s[14:15], v66, v66, 1.0
	v_rcp_f32_e32 v68, v67
	v_readlane_b32 s14, v254, 49
	v_readlane_b32 s15, v254, 50
	v_fma_f32 v69, -v67, v68, 1.0
	v_fmac_f32_e32 v68, v69, v68
	v_div_scale_f32 v69, vcc, 1.0, v66, 1.0
	v_mul_f32_e32 v70, v69, v68
	v_fma_f32 v71, -v67, v70, v69
	v_fmac_f32_e32 v70, v71, v68
	v_fma_f32 v67, -v67, v70, v69
	v_div_fmas_f32 v67, v67, v68, v70
	v_div_fixup_f32 v70, v67, v66, 1.0
	v_pk_mul_f32 v[66:67], v[116:117], v[70:71] op_sel_hi:[1,0]
	v_pk_mul_f32 v[68:69], v[112:113], v[70:71] op_sel_hi:[1,0]
	v_pk_mul_f32 v[66:67], v[4:5], v[66:67]
	v_pk_mul_f32 v[68:69], v[2:3], v[68:69]
	s_waitcnt vmcnt(0)
	v_mov_b64_e32 v[80:81], v[64:65]
	v_mov_b64_e32 v[78:79], v[62:63]
	v_pk_fma_f32 v[72:73], v[20:21], v[66:67], v[24:25]
	v_pk_fma_f32 v[66:67], v[18:19], v[68:69], v[22:23]
	v_pk_mul_f32 v[68:69], v[114:115], v[70:71] op_sel_hi:[1,0]
	v_pk_mul_f32 v[74:75], v[110:111], v[70:71] op_sel_hi:[1,0]
	v_pk_mul_f32 v[68:69], v[8:9], v[68:69]
	v_pk_mul_f32 v[74:75], v[6:7], v[74:75]
	v_pk_fma_f32 v[76:77], v[32:33], v[68:69], v[28:29]
	v_pk_fma_f32 v[68:69], v[30:31], v[74:75], v[26:27]
	v_cvt_pk_bf16_f32 v66, v66, v67
	v_cvt_pk_bf16_f32 v67, v72, v73
	v_lshl_add_u64 v[72:73], s[6:7], 0, v[96:97]
	v_cvt_pk_bf16_f32 v68, v68, v69
	v_cvt_pk_bf16_f32 v69, v76, v77
	global_store_dwordx4 v[72:73], v[66:69], off
	s_nop 1
	v_pk_mul_f32 v[66:67], v[108:109], v[70:71] op_sel_hi:[1,0]
	v_pk_mul_f32 v[68:69], v[106:107], v[70:71] op_sel_hi:[1,0]
	v_pk_mul_f32 v[66:67], v[12:13], v[66:67]
	v_pk_mul_f32 v[68:69], v[10:11], v[68:69]
	v_pk_fma_f32 v[72:73], v[44:45], v[66:67], v[36:37]
	v_pk_fma_f32 v[66:67], v[42:43], v[68:69], v[34:35]
	v_pk_mul_f32 v[68:69], v[104:105], v[70:71] op_sel_hi:[1,0]
	v_pk_mul_f32 v[70:71], v[102:103], v[70:71] op_sel_hi:[1,0]
	v_pk_mul_f32 v[68:69], v[16:17], v[68:69]
	v_pk_mul_f32 v[70:71], v[14:15], v[70:71]
	v_pk_fma_f32 v[74:75], v[48:49], v[68:69], v[40:41]
	v_pk_fma_f32 v[68:69], v[46:47], v[70:71], v[38:39]
	v_cvt_pk_bf16_f32 v66, v66, v67
	v_cvt_pk_bf16_f32 v67, v72, v73
	v_lshl_add_u64 v[70:71], s[6:7], 0, v[0:1]
	v_cvt_pk_bf16_f32 v68, v68, v69
	v_cvt_pk_bf16_f32 v69, v74, v75
	global_store_dwordx4 v[70:71], v[66:69], off
	s_add_u32 s6, s6, s14
	v_mov_b64_e32 v[76:77], v[56:57]
	v_mov_b64_e32 v[72:73], v[52:53]
	v_mov_b64_e32 v[68:69], v[60:61]
	s_addc_u32 s7, s7, s15
	s_andn2_b64 vcc, exec, s[12:13]
	v_mov_b64_e32 v[74:75], v[54:55]
	v_mov_b64_e32 v[70:71], v[50:51]
	v_mov_b64_e32 v[66:67], v[58:59]
	s_mov_b32 s14, s10
	s_cbranch_vccz .LBB0_561
